# WG stagger variant: 14us delay for half the workgroups at the four GEMM phase entries
# baseline (speedup 1.0000x reference)
;   DI bf16_t* wt_in0() const { return (bf16_t*)(ws + OFF_WT_IN0); }
;   DI bf16_t* h() const { return (bf16_t*)(ws + OFF_H); }
; DI void phase_gemm_in0(const Params& p, char* smem) {
;   u32x4 ra[4], rb[4]; bool pre = false;
;   for (int t = blockIdx.x; t < 64 * 16; t += gridDim.x) {
;     const int mt = t & 63, nt = t >> 6, tn = t + gridDim.x;
;     const bool has_next = tn < 64 * 16;
;     const GTile tl{p.h(), D, p.wt_in0(), D, D, mt * 256, nt * 256}, nx{p.h(), D, p.wt_in0(), D, D, (tn & 63) * 256, (tn >> 6) * 256};
.Lgs_185:
	s_or_b64 exec, exec, s[0:1]
	s_bitcmp1_b32 s84, 3
	s_cbranch_scc0 .Lstag_1
	s_sleep 127
	s_sleep 127
	s_sleep 127
	s_sleep 127
